# P9/P13 sandwich rows: x loads hoisted to row top, split-K slab adds pipelined (rolling 16-deep), store/load order swapped
# baseline (speedup 1.0000x reference)
.LBB0_1557:
	s_waitcnt vmcnt(15)
	v_pk_mul_f32 v[128:129], v[52:53], v[52:53]
	v_pk_mul_f32 v[132:133], v[50:51], v[50:51]
	s_and_b64 s[20:21], s[20:21], exec
	v_pk_mov_b32 v[134:135], v[132:133], v[128:129] op_sel:[1,0]
	v_mov_b32_e32 v133, v129
	v_pk_add_f32 v[128:129], v[134:135], v[132:133]
	s_waitcnt vmcnt(14)
	v_pk_mul_f32 v[132:133], v[60:61], v[60:61]
	v_pk_add_f32 v[128:129], v[128:129], v[128:129] op_sel_hi:[0,1]
	v_pk_mul_f32 v[134:135], v[58:59], v[58:59]
	s_waitcnt vmcnt(13)
	v_mul_f32_e32 v128, v54, v54
	v_pk_mov_b32 v[136:137], v[134:135], v[132:133] op_sel:[1,0]
	v_mov_b32_e32 v135, v133
	v_pk_add_f32 v[132:133], v[136:137], v[134:135]
	v_pk_fma_f32 v[134:135], v[54:55], v[54:55], v[128:129] op_sel_hi:[1,1,0]
	v_mul_f32_e32 v128, v56, v56
	v_pk_add_f32 v[132:133], v[132:133], v[132:133] op_sel_hi:[0,1]
	v_pk_fma_f32 v[136:137], v[56:57], v[56:57], v[128:129] op_sel_hi:[1,1,0]
	s_waitcnt vmcnt(12)
	v_mul_f32_e32 v134, v46, v46
	v_mul_f32_e32 v136, v47, v47
	v_mul_f32_e32 v132, v48, v48
	v_mul_f32_e32 v128, v49, v49
	v_pk_add_f32 v[134:135], v[134:135], v[136:137]
	v_pk_add_f32 v[128:129], v[132:133], v[128:129]
	s_waitcnt vmcnt(11)
	v_pk_mul_f32 v[132:133], v[32:33], v[32:33]
	v_pk_add_f32 v[128:129], v[134:135], v[128:129]
	v_pk_mul_f32 v[134:135], v[30:31], v[30:31]
	v_pk_add_f32 v[128:129], v[128:129], v[128:129] op_sel_hi:[0,1]
	v_pk_mov_b32 v[136:137], v[134:135], v[132:133] op_sel:[1,0]
	v_mov_b32_e32 v135, v133
	s_waitcnt vmcnt(10)
	v_mul_f32_e32 v128, v38, v38
	v_pk_add_f32 v[132:133], v[136:137], v[134:135]
	v_pk_fma_f32 v[134:135], v[38:39], v[38:39], v[128:129] op_sel_hi:[1,1,0]
	v_mul_f32_e32 v128, v40, v40
	v_pk_add_f32 v[132:133], v[132:133], v[132:133] op_sel_hi:[0,1]
	v_pk_fma_f32 v[136:137], v[40:41], v[40:41], v[128:129] op_sel_hi:[1,1,0]
	s_waitcnt vmcnt(9)
	v_mul_f32_e32 v134, v42, v42
	v_mul_f32_e32 v136, v43, v43
	v_mul_f32_e32 v132, v44, v44
	v_mul_f32_e32 v128, v45, v45
	v_pk_add_f32 v[134:135], v[134:135], v[136:137]
	v_pk_add_f32 v[128:129], v[132:133], v[128:129]
	s_waitcnt vmcnt(8)
	v_pk_mul_f32 v[132:133], v[36:37], v[36:37]
	v_pk_add_f32 v[128:129], v[134:135], v[128:129]
	v_pk_mul_f32 v[134:135], v[34:35], v[34:35]
	v_pk_add_f32 v[128:129], v[128:129], v[128:129] op_sel_hi:[0,1]
	v_pk_mov_b32 v[136:137], v[134:135], v[132:133] op_sel:[1,0]
	v_mov_b32_e32 v135, v133
	s_waitcnt vmcnt(7)
	v_mul_f32_e32 v128, v26, v26
	s_cselect_b32 s21, 0, s15
	s_cselect_b32 s20, s24, s14
	v_pk_add_f32 v[132:133], v[136:137], v[134:135]
	v_pk_fma_f32 v[134:135], v[26:27], v[26:27], v[128:129] op_sel_hi:[1,1,0]
	v_mul_f32_e32 v128, v28, v28
	s_cselect_b32 s24, s7, s5
	s_cselect_b32 s25, s6, s4
	s_lshl_b64 s[20:21], s[20:21], 14
	v_pk_add_f32 v[132:133], v[132:133], v[132:133] op_sel_hi:[0,1]
	v_pk_fma_f32 v[136:137], v[28:29], v[28:29], v[128:129] op_sel_hi:[1,1,0]
	s_add_u32 s20, s25, s20
	s_waitcnt vmcnt(6)
	v_mul_f32_e32 v134, v22, v22
	v_mul_f32_e32 v136, v23, v23
	v_mul_f32_e32 v132, v24, v24
	v_mul_f32_e32 v128, v25, v25
	s_addc_u32 s21, s24, s21
	v_pk_add_f32 v[134:135], v[134:135], v[136:137]
	v_pk_add_f32 v[128:129], v[132:133], v[128:129]
	s_waitcnt vmcnt(5)
	v_pk_mul_f32 v[132:133], v[20:21], v[20:21]
	v_pk_add_f32 v[128:129], v[134:135], v[128:129]
	global_load_dwordx4 v[138:141], v[70:71], off
	v_pk_add_f32 v[128:129], v[128:129], v[128:129] op_sel_hi:[0,1]
	v_pk_mul_f32 v[142:143], v[18:19], v[18:19]
	s_waitcnt vmcnt(5)
	v_mul_f32_e32 v128, v14, v14
	v_pk_mov_b32 v[144:145], v[142:143], v[132:133] op_sel:[1,0]
	v_mov_b32_e32 v143, v133
	v_pk_add_f32 v[132:133], v[144:145], v[142:143]
	v_pk_fma_f32 v[142:143], v[14:15], v[14:15], v[128:129] op_sel_hi:[1,1,0]
	v_mul_f32_e32 v128, v16, v16
	v_pk_add_f32 v[132:133], v[132:133], v[132:133] op_sel_hi:[0,1]
	v_pk_fma_f32 v[144:145], v[16:17], v[16:17], v[128:129] op_sel_hi:[1,1,0]
	s_waitcnt vmcnt(4)
	v_mul_f32_e32 v142, v10, v10
	v_mul_f32_e32 v144, v11, v11
	v_mul_f32_e32 v132, v12, v12
	v_mul_f32_e32 v128, v13, v13
	v_pk_add_f32 v[142:143], v[142:143], v[144:145]
	v_pk_add_f32 v[128:129], v[132:133], v[128:129]
	s_waitcnt vmcnt(3)
	v_pk_mul_f32 v[132:133], v[4:5], v[4:5]
	v_pk_add_f32 v[128:129], v[142:143], v[128:129]
	v_pk_mul_f32 v[142:143], v[2:3], v[2:3]
	v_pk_add_f32 v[128:129], v[128:129], v[128:129] op_sel_hi:[0,1]
	v_pk_mov_b32 v[144:145], v[142:143], v[132:133] op_sel:[1,0]
	v_mov_b32_e32 v143, v133
	s_waitcnt vmcnt(2)
	v_mul_f32_e32 v128, v6, v6
	v_pk_add_f32 v[132:133], v[144:145], v[142:143]
	v_pk_fma_f32 v[142:143], v[6:7], v[6:7], v[128:129] op_sel_hi:[1,1,0]
	v_mul_f32_e32 v128, v8, v8
	v_pk_add_f32 v[132:133], v[132:133], v[132:133] op_sel_hi:[0,1]
	v_pk_fma_f32 v[144:145], v[8:9], v[8:9], v[128:129] op_sel_hi:[1,1,0]
	s_waitcnt vmcnt(1)
	v_mul_f32_e32 v142, v62, v62
	v_mul_f32_e32 v144, v63, v63
	v_mul_f32_e32 v132, v64, v64
	v_mul_f32_e32 v128, v65, v65
	v_pk_add_f32 v[142:143], v[142:143], v[144:145]
	v_pk_add_f32 v[128:129], v[132:133], v[128:129]
	v_lshl_add_u64 v[132:133], s[28:29], 0, v[124:125]
	v_pk_add_f32 v[128:129], v[142:143], v[128:129]
	v_lshl_add_u64 v[142:143], s[20:21], 0, v[66:67]
	v_add_f32_e32 v128, v128, v129
	ds_bpermute_b32 v129, v156, v128
	v_add_co_u32_e32 v144, vcc, s27, v142
	s_add_u32 s14, s14, s40
	s_nop 0
	v_addc_co_u32_e32 v145, vcc, 0, v143, vcc
	s_waitcnt lgkmcnt(0)
	v_add_f32_e32 v128, v128, v129
	ds_bpermute_b32 v129, v157, v128
	v_add_co_u32_e32 v146, vcc, s27, v132
	s_addc_u32 s15, s15, s41
	s_nop 0
	v_addc_co_u32_e32 v147, vcc, 0, v133, vcc
	s_waitcnt lgkmcnt(0)
	v_add_f32_e32 v128, v128, v129
	ds_bpermute_b32 v129, v158, v128
	v_add_co_u32_e32 v148, vcc, s52, v142
	v_lshl_add_u64 v[122:123], v[122:123], 0, s[8:9]
	s_nop 0
	v_addc_co_u32_e32 v149, vcc, 0, v143, vcc
	s_waitcnt lgkmcnt(0)
	v_add_f32_e32 v128, v128, v129
	ds_bpermute_b32 v129, v159, v128
	v_add_co_u32_e32 v150, vcc, s52, v132
	s_cmpk_lt_i32 s14, 0x2400
	s_nop 0
	v_addc_co_u32_e32 v151, vcc, 0, v133, vcc
	s_waitcnt lgkmcnt(0)
	v_add_f32_e32 v128, v128, v129
	ds_bpermute_b32 v129, v160, v128
	v_add_co_u32_e32 v142, vcc, s53, v142
	v_lshl_add_u64 v[124:125], v[124:125], 0, s[10:11]
	s_nop 0
	v_addc_co_u32_e32 v143, vcc, 0, v143, vcc
	s_waitcnt lgkmcnt(0)
	v_add_f32_e32 v128, v128, v129
	ds_bpermute_b32 v129, v161, v128
	s_waitcnt lgkmcnt(0)
	v_add_f32_e32 v128, v128, v129
	v_fmamk_f32 v128, v128, 0x39800000, v131
	v_rsq_f32_e32 v128, v128
	s_nop 0
	v_pk_mul_f32 v[50:51], v[50:51], v[128:129] op_sel_hi:[1,0]
	v_pk_mul_f32 v[52:53], v[52:53], v[128:129] op_sel_hi:[1,0]
	s_waitcnt vmcnt(0)
	v_pk_fma_f32 v[50:51], v[138:139], v[50:51], v[202:203]
	v_pk_fma_f32 v[52:53], v[140:141], v[52:53], v[204:205]
	global_load_dwordx4 v[138:141], v[70:71], off offset:1024
	v_pk_mul_f32 v[60:61], v[60:61], v[128:129] op_sel_hi:[1,0]
	v_pk_mul_f32 v[58:59], v[58:59], v[128:129] op_sel_hi:[1,0]
	v_pk_mul_f32 v[56:57], v[56:57], v[128:129] op_sel_hi:[1,0]
	v_pk_mul_f32 v[54:55], v[54:55], v[128:129] op_sel_hi:[1,0]
	v_pk_mul_f32 v[46:47], v[46:47], v[128:129] op_sel_hi:[1,0]
	v_pk_mul_f32 v[48:49], v[48:49], v[128:129] op_sel_hi:[1,0]
	v_pk_mul_f32 v[32:33], v[32:33], v[128:129] op_sel_hi:[1,0]
	v_pk_mul_f32 v[30:31], v[30:31], v[128:129] op_sel_hi:[1,0]
	v_pk_mul_f32 v[40:41], v[40:41], v[128:129] op_sel_hi:[1,0]
	v_pk_mul_f32 v[38:39], v[38:39], v[128:129] op_sel_hi:[1,0]
	v_pk_mul_f32 v[42:43], v[42:43], v[128:129] op_sel_hi:[1,0]
	v_pk_mul_f32 v[44:45], v[44:45], v[128:129] op_sel_hi:[1,0]
	v_pk_mul_f32 v[36:37], v[36:37], v[128:129] op_sel_hi:[1,0]
	v_pk_mul_f32 v[34:35], v[34:35], v[128:129] op_sel_hi:[1,0]
	v_pk_mul_f32 v[28:29], v[28:29], v[128:129] op_sel_hi:[1,0]
	v_pk_mul_f32 v[26:27], v[26:27], v[128:129] op_sel_hi:[1,0]
	v_pk_mul_f32 v[22:23], v[22:23], v[128:129] op_sel_hi:[1,0]
	v_pk_mul_f32 v[24:25], v[24:25], v[128:129] op_sel_hi:[1,0]
	v_pk_mul_f32 v[20:21], v[20:21], v[128:129] op_sel_hi:[1,0]
	v_pk_mul_f32 v[18:19], v[18:19], v[128:129] op_sel_hi:[1,0]
	v_pk_mul_f32 v[16:17], v[16:17], v[128:129] op_sel_hi:[1,0]
	v_pk_mul_f32 v[14:15], v[14:15], v[128:129] op_sel_hi:[1,0]
	v_pk_mul_f32 v[10:11], v[10:11], v[128:129] op_sel_hi:[1,0]
	v_pk_mul_f32 v[12:13], v[12:13], v[128:129] op_sel_hi:[1,0]
	v_pk_mul_f32 v[4:5], v[4:5], v[128:129] op_sel_hi:[1,0]
	v_pk_mul_f32 v[2:3], v[2:3], v[128:129] op_sel_hi:[1,0]
	v_pk_mul_f32 v[8:9], v[8:9], v[128:129] op_sel_hi:[1,0]
	v_pk_mul_f32 v[6:7], v[6:7], v[128:129] op_sel_hi:[1,0]
	v_pk_mul_f32 v[62:63], v[62:63], v[128:129] op_sel_hi:[1,0]
	v_pk_mul_f32 v[64:65], v[64:65], v[128:129] op_sel_hi:[1,0]
	v_pk_mul_f32 v[128:129], v[52:53], v[52:53]
	global_store_dwordx4 v[132:133], v[50:53], off
	s_waitcnt vmcnt(1)
	v_pk_fma_f32 v[58:59], v[138:139], v[58:59], v[206:207]
	v_pk_fma_f32 v[60:61], v[140:141], v[60:61], v[208:209]
	global_load_dwordx4 v[138:141], v[70:71], off offset:2048
	global_store_dwordx4 v[132:133], v[58:61], off offset:1024
	s_waitcnt vmcnt(1)
	v_pk_fma_f32 v[54:55], v[138:139], v[54:55], v[210:211]
	v_pk_fma_f32 v[56:57], v[140:141], v[56:57], v[212:213]
	global_load_dwordx4 v[138:141], v[70:71], off offset:3072
	global_store_dwordx4 v[132:133], v[54:57], off offset:2048
	s_waitcnt vmcnt(1)
	v_pk_fma_f32 v[48:49], v[140:141], v[48:49], v[216:217]
	v_pk_fma_f32 v[46:47], v[138:139], v[46:47], v[214:215]
	global_load_dwordx4 v[138:141], v[72:73], off
	global_store_dwordx4 v[132:133], v[46:49], off offset:3072
	s_waitcnt vmcnt(1)
	v_pk_fma_f32 v[30:31], v[138:139], v[30:31], v[218:219]
	v_pk_fma_f32 v[32:33], v[140:141], v[32:33], v[220:221]
	global_load_dwordx4 v[138:141], v[74:75], off
	global_store_dwordx4 v[146:147], v[30:33], off offset:-4096
	s_waitcnt vmcnt(1)
	v_pk_fma_f32 v[38:39], v[138:139], v[38:39], v[222:223]
	v_pk_fma_f32 v[40:41], v[140:141], v[40:41], v[224:225]
	global_load_dwordx4 v[138:141], v[76:77], off
	global_store_dwordx4 v[150:151], v[38:41], off offset:1024
	s_waitcnt vmcnt(1)
	v_pk_fma_f32 v[44:45], v[140:141], v[44:45], v[228:229]
	v_pk_fma_f32 v[42:43], v[138:139], v[42:43], v[226:227]
	global_load_dwordx4 v[138:141], v[78:79], off
	global_store_dwordx4 v[150:151], v[42:45], off offset:2048
	s_waitcnt vmcnt(1)
	v_pk_fma_f32 v[34:35], v[138:139], v[34:35], v[230:231]
	v_pk_fma_f32 v[36:37], v[140:141], v[36:37], v[232:233]
	global_load_dwordx4 v[138:141], v[80:81], off
	global_store_dwordx4 v[150:151], v[34:37], off offset:3072
	s_waitcnt vmcnt(1)
	v_pk_fma_f32 v[26:27], v[26:27], v[138:139], v[234:235]
	v_pk_fma_f32 v[28:29], v[28:29], v[140:141], v[236:237]
	global_load_dwordx4 v[138:141], v[82:83], off
	global_store_dwordx4 v[146:147], v[26:29], off
	s_waitcnt vmcnt(1)
	v_pk_fma_f32 v[24:25], v[24:25], v[140:141], v[240:241]
	v_pk_fma_f32 v[22:23], v[22:23], v[138:139], v[238:239]
	global_load_dwordx4 v[138:141], v[84:85], off
	global_store_dwordx4 v[146:147], v[22:25], off offset:1024
	s_waitcnt vmcnt(1)
	v_pk_fma_f32 v[18:19], v[18:19], v[138:139], v[182:183]
	v_pk_fma_f32 v[20:21], v[20:21], v[140:141], v[184:185]
	global_load_dwordx4 v[138:141], v[86:87], off
	v_add_co_u32_e32 v144, vcc, s53, v132
	global_store_dwordx4 v[146:147], v[18:21], off offset:2048
	s_waitcnt vmcnt(1)
	v_pk_fma_f32 v[14:15], v[14:15], v[138:139], v[186:187]
	v_pk_fma_f32 v[16:17], v[16:17], v[140:141], v[188:189]
	global_load_dwordx4 v[138:141], v[88:89], off
	v_addc_co_u32_e32 v145, vcc, 0, v133, vcc
	global_store_dwordx4 v[146:147], v[14:17], off offset:3072
	s_waitcnt vmcnt(1)
	v_pk_fma_f32 v[12:13], v[12:13], v[140:141], v[192:193]
	v_pk_fma_f32 v[10:11], v[10:11], v[138:139], v[190:191]
	global_load_dwordx4 v[136:139], v[90:91], off
	v_pk_mul_f32 v[140:141], v[50:51], v[50:51]
	global_store_dwordx4 v[144:145], v[10:13], off
	s_waitcnt vmcnt(1)
	v_pk_fma_f32 v[2:3], v[2:3], v[136:137], v[194:195]
	v_pk_fma_f32 v[4:5], v[4:5], v[138:139], v[196:197]
	global_load_dwordx4 v[136:139], v[92:93], off
	global_store_dwordx4 v[144:145], v[2:5], off offset:1024
	s_waitcnt vmcnt(1)
	v_pk_fma_f32 v[6:7], v[6:7], v[136:137], v[244:245]
	v_pk_fma_f32 v[8:9], v[8:9], v[138:139], v[246:247]
	global_load_dwordx4 v[136:139], v[94:95], off
	v_pk_mov_b32 v[142:143], v[140:141], v[128:129] op_sel:[1,0]
	v_mov_b32_e32 v141, v129
	v_pk_add_f32 v[128:129], v[142:143], v[140:141]
	v_pk_mul_f32 v[140:141], v[58:59], v[58:59]
	v_pk_mul_f32 v[142:143], v[60:61], v[60:61]
	v_pk_add_f32 v[128:129], v[128:129], v[128:129] op_sel_hi:[0,1]
	v_pk_mov_b32 v[146:147], v[140:141], v[142:143] op_sel:[1,0]
	v_mov_b32_e32 v141, v143
	v_pk_add_f32 v[140:141], v[146:147], v[140:141]
	v_mul_f32_e32 v128, v54, v54
	v_pk_add_f32 v[140:141], v[140:141], v[140:141] op_sel_hi:[0,1]
	v_mul_f32_e32 v140, v56, v56
	v_pk_fma_f32 v[142:143], v[54:55], v[54:55], v[128:129] op_sel_hi:[1,1,0]
	v_pk_fma_f32 v[146:147], v[56:57], v[56:57], v[140:141] op_sel_hi:[1,1,0]
	v_mul_f32_e32 v142, v46, v46
	v_mul_f32_e32 v146, v47, v47
	v_mul_f32_e32 v128, v48, v48
	v_mul_f32_e32 v140, v49, v49
	v_pk_add_f32 v[142:143], v[142:143], v[146:147]
	v_pk_add_f32 v[128:129], v[128:129], v[140:141]
	v_pk_mul_f32 v[140:141], v[30:31], v[30:31]
	v_pk_add_f32 v[128:129], v[142:143], v[128:129]
	v_pk_mul_f32 v[142:143], v[32:33], v[32:33]
	v_pk_add_f32 v[128:129], v[128:129], v[128:129] op_sel_hi:[0,1]
	v_pk_mov_b32 v[146:147], v[140:141], v[142:143] op_sel:[1,0]
	v_mov_b32_e32 v141, v143
	v_pk_add_f32 v[140:141], v[146:147], v[140:141]
	v_mul_f32_e32 v128, v38, v38
	v_pk_add_f32 v[140:141], v[140:141], v[140:141] op_sel_hi:[0,1]
	v_mul_f32_e32 v140, v40, v40
	v_pk_fma_f32 v[142:143], v[38:39], v[38:39], v[128:129] op_sel_hi:[1,1,0]
	v_pk_fma_f32 v[146:147], v[40:41], v[40:41], v[140:141] op_sel_hi:[1,1,0]
	v_mul_f32_e32 v142, v42, v42
	v_mul_f32_e32 v146, v43, v43
	v_mul_f32_e32 v140, v44, v44
	v_mul_f32_e32 v128, v45, v45
	v_pk_add_f32 v[142:143], v[142:143], v[146:147]
	v_pk_add_f32 v[128:129], v[140:141], v[128:129]
	v_pk_mul_f32 v[140:141], v[34:35], v[34:35]
	v_pk_add_f32 v[128:129], v[142:143], v[128:129]
	v_pk_mul_f32 v[142:143], v[36:37], v[36:37]
	v_pk_add_f32 v[128:129], v[128:129], v[128:129] op_sel_hi:[0,1]
	v_pk_mov_b32 v[146:147], v[140:141], v[142:143] op_sel:[1,0]
	v_mov_b32_e32 v141, v143
	v_pk_add_f32 v[140:141], v[146:147], v[140:141]
	v_mul_f32_e32 v128, v26, v26
	v_pk_add_f32 v[140:141], v[140:141], v[140:141] op_sel_hi:[0,1]
	v_mul_f32_e32 v140, v28, v28
	v_pk_fma_f32 v[142:143], v[26:27], v[26:27], v[128:129] op_sel_hi:[1,1,0]
	v_pk_fma_f32 v[146:147], v[28:29], v[28:29], v[140:141] op_sel_hi:[1,1,0]
	v_mul_f32_e32 v142, v22, v22
	v_mul_f32_e32 v146, v23, v23
	v_mul_f32_e32 v140, v24, v24
	v_mul_f32_e32 v128, v25, v25
	v_pk_add_f32 v[142:143], v[142:143], v[146:147]
	v_pk_add_f32 v[128:129], v[140:141], v[128:129]
	v_pk_mul_f32 v[140:141], v[18:19], v[18:19]
	v_pk_add_f32 v[128:129], v[142:143], v[128:129]
	v_pk_mul_f32 v[142:143], v[20:21], v[20:21]
	v_pk_add_f32 v[128:129], v[128:129], v[128:129] op_sel:[0,1] op_sel_hi:[1,0]
	v_pk_mov_b32 v[146:147], v[140:141], v[142:143] op_sel:[1,0]
	v_mov_b32_e32 v141, v143
	v_pk_add_f32 v[140:141], v[146:147], v[140:141]
	v_mul_f32_e32 v142, v15, v15
	v_mul_f32_e32 v146, v17, v17
	v_pk_add_f32 v[140:141], v[140:141], v[140:141] op_sel:[0,1] op_sel_hi:[1,0]
	v_pk_fma_f32 v[142:143], v[14:15], v[14:15], v[142:143] op_sel_hi:[1,1,0]
	v_mul_f32_e32 v129, v10, v10
	v_mul_f32_e32 v141, v11, v11
	v_mul_f32_e32 v143, v12, v12
	v_pk_add_f32 v[128:129], v[128:129], v[140:141]
	global_store_dwordx4 v[144:145], v[6:9], off offset:2048
	s_waitcnt vmcnt(1)
	v_pk_fma_f32 v[64:65], v[64:65], v[138:139], v[250:251]
	v_pk_fma_f32 v[62:63], v[62:63], v[136:137], v[248:249]
	global_store_dwordx4 v[144:145], v[62:65], off offset:3072
	global_load_dwordx4 v[132:135], v[96:97], off
	v_pk_fma_f32 v[136:137], v[16:17], v[16:17], v[146:147] op_sel_hi:[1,1,0]
	v_mul_f32_e32 v139, v13, v13
	v_mov_b32_e32 v137, v139
	v_pk_add_f32 v[136:137], v[142:143], v[136:137]
	v_pk_mul_f32 v[138:139], v[4:5], v[4:5]
	v_pk_add_f32 v[128:129], v[128:129], v[136:137]
	v_pk_mul_f32 v[136:137], v[2:3], v[2:3]
	v_pk_add_f32 v[128:129], v[128:129], v[128:129] op_sel:[0,1] op_sel_hi:[1,0]
	v_pk_mov_b32 v[140:141], v[136:137], v[138:139] op_sel:[1,0]
	v_mov_b32_e32 v137, v139
	v_pk_add_f32 v[136:137], v[140:141], v[136:137]
	v_mul_f32_e32 v138, v7, v7
	v_mul_f32_e32 v140, v9, v9
	v_pk_add_f32 v[136:137], v[136:137], v[136:137] op_sel:[0,1] op_sel_hi:[1,0]
	v_pk_fma_f32 v[138:139], v[6:7], v[6:7], v[138:139] op_sel_hi:[1,1,0]
	v_pk_fma_f32 v[140:141], v[8:9], v[8:9], v[140:141] op_sel_hi:[1,1,0]
	v_mul_f32_e32 v129, v62, v62
	v_mul_f32_e32 v137, v63, v63
	v_mul_f32_e32 v139, v64, v64
	v_mul_f32_e32 v141, v65, v65
	v_pk_add_f32 v[128:129], v[128:129], v[136:137]
	v_pk_add_f32 v[136:137], v[138:139], v[140:141]
	s_nop 0
	v_pk_add_f32 v[128:129], v[128:129], v[136:137]
	v_add_co_u32_e32 v136, vcc, s63, v126
	v_add_f32_e32 v128, v128, v129
	ds_bpermute_b32 v129, v156, v128
	v_addc_co_u32_e32 v137, vcc, 0, v127, vcc
	v_add_co_u32_e32 v126, vcc, s62, v126
	s_waitcnt lgkmcnt(0)
	v_add_f32_e32 v128, v128, v129
	ds_bpermute_b32 v129, v157, v128
	v_addc_co_u32_e32 v127, vcc, 0, v127, vcc
	s_waitcnt lgkmcnt(0)
	v_add_f32_e32 v128, v128, v129
	ds_bpermute_b32 v129, v158, v128
	s_waitcnt lgkmcnt(0)
	v_add_f32_e32 v128, v128, v129
	ds_bpermute_b32 v129, v159, v128
	s_waitcnt lgkmcnt(0)
	v_add_f32_e32 v128, v128, v129
	ds_bpermute_b32 v129, v160, v128
	s_waitcnt lgkmcnt(0)
	v_add_f32_e32 v128, v128, v129
	ds_bpermute_b32 v129, v161, v128
	s_waitcnt lgkmcnt(0)
	v_add_f32_e32 v128, v128, v129
	v_fmamk_f32 v128, v128, 0x39800000, v131
	v_rsq_f32_e32 v128, v128
	s_nop 0
	v_pk_mul_f32 v[50:51], v[50:51], v[128:129] op_sel_hi:[1,0]
	v_pk_mul_f32 v[52:53], v[52:53], v[128:129] op_sel_hi:[1,0]
	v_pk_mul_f32 v[58:59], v[58:59], v[128:129] op_sel_hi:[1,0]
	v_pk_mul_f32 v[60:61], v[60:61], v[128:129] op_sel_hi:[1,0]
	v_pk_mul_f32 v[54:55], v[54:55], v[128:129] op_sel_hi:[1,0]
	v_pk_mul_f32 v[56:57], v[56:57], v[128:129] op_sel_hi:[1,0]
	v_pk_mul_f32 v[46:47], v[46:47], v[128:129] op_sel_hi:[1,0]
	v_pk_mul_f32 v[48:49], v[48:49], v[128:129] op_sel_hi:[1,0]
	v_pk_mul_f32 v[30:31], v[30:31], v[128:129] op_sel_hi:[1,0]
	v_pk_mul_f32 v[32:33], v[32:33], v[128:129] op_sel_hi:[1,0]
	v_pk_mul_f32 v[38:39], v[38:39], v[128:129] op_sel_hi:[1,0]
	s_waitcnt vmcnt(0)
	v_pk_mul_f32 v[50:51], v[132:133], v[50:51]
	v_pk_mul_f32 v[52:53], v[134:135], v[52:53]
	v_cvt_pk_bf16_f32 v50, v50, v51
	v_cvt_pk_bf16_f32 v51, v52, v53
	global_store_dwordx2 v[136:137], v[50:51], off offset:-4096
	global_load_dwordx4 v[50:53], v[96:97], off offset:1024
	v_pk_mul_f32 v[40:41], v[40:41], v[128:129] op_sel_hi:[1,0]
	v_pk_mul_f32 v[34:35], v[34:35], v[128:129] op_sel_hi:[1,0]
	v_pk_mul_f32 v[36:37], v[36:37], v[128:129] op_sel_hi:[1,0]
	v_pk_mul_f32 v[26:27], v[26:27], v[128:129] op_sel_hi:[1,0]
	v_pk_mul_f32 v[28:29], v[28:29], v[128:129] op_sel_hi:[1,0]
	v_pk_mul_f32 v[22:23], v[22:23], v[128:129] op_sel_hi:[1,0]
	v_pk_mul_f32 v[24:25], v[24:25], v[128:129] op_sel_hi:[1,0]
	v_pk_mul_f32 v[18:19], v[18:19], v[128:129] op_sel_hi:[1,0]
	v_pk_mul_f32 v[20:21], v[20:21], v[128:129] op_sel_hi:[1,0]
	v_pk_mul_f32 v[14:15], v[14:15], v[128:129] op_sel_hi:[1,0]
	v_pk_mul_f32 v[16:17], v[16:17], v[128:129] op_sel_hi:[1,0]
	v_pk_mul_f32 v[10:11], v[10:11], v[128:129] op_sel_hi:[1,0]
	v_pk_mul_f32 v[12:13], v[12:13], v[128:129] op_sel_hi:[1,0]
	v_pk_mul_f32 v[2:3], v[2:3], v[128:129] op_sel_hi:[1,0]
	v_pk_mul_f32 v[4:5], v[4:5], v[128:129] op_sel_hi:[1,0]
	v_pk_mul_f32 v[6:7], v[6:7], v[128:129] op_sel_hi:[1,0]
	v_pk_mul_f32 v[8:9], v[8:9], v[128:129] op_sel_hi:[1,0]
	s_waitcnt vmcnt(0)
	v_pk_mul_f32 v[50:51], v[50:51], v[58:59]
	v_pk_mul_f32 v[52:53], v[52:53], v[60:61]
	v_cvt_pk_bf16_f32 v50, v50, v51
	v_cvt_pk_bf16_f32 v51, v52, v53
	global_store_dwordx2 v[126:127], v[50:51], off offset:512
	global_load_dwordx4 v[50:53], v[96:97], off offset:2048
	s_waitcnt vmcnt(0)
	v_pk_mul_f32 v[50:51], v[50:51], v[54:55]
	v_pk_mul_f32 v[52:53], v[52:53], v[56:57]
	v_cvt_pk_bf16_f32 v50, v50, v51
	v_cvt_pk_bf16_f32 v51, v52, v53
	global_store_dwordx2 v[126:127], v[50:51], off offset:1024
	global_load_dwordx4 v[50:53], v[96:97], off offset:3072
	s_waitcnt vmcnt(0)
	v_pk_mul_f32 v[46:47], v[50:51], v[46:47]
	v_pk_mul_f32 v[48:49], v[52:53], v[48:49]
	v_cvt_pk_bf16_f32 v46, v46, v47
	v_cvt_pk_bf16_f32 v47, v48, v49
	global_store_dwordx2 v[126:127], v[46:47], off offset:1536
	global_load_dwordx4 v[46:49], v[98:99], off
	s_waitcnt vmcnt(0)
	v_pk_mul_f32 v[30:31], v[46:47], v[30:31]
	v_pk_mul_f32 v[32:33], v[48:49], v[32:33]
	v_cvt_pk_bf16_f32 v30, v30, v31
	v_cvt_pk_bf16_f32 v31, v32, v33
	global_store_dwordx2 v[126:127], v[30:31], off offset:2048
	global_load_dwordx4 v[30:33], v[100:101], off
	s_waitcnt vmcnt(0)
	v_pk_mul_f32 v[30:31], v[38:39], v[30:31]
	v_pk_mul_f32 v[32:33], v[40:41], v[32:33]
	v_cvt_pk_bf16_f32 v30, v30, v31
	v_cvt_pk_bf16_f32 v31, v32, v33
	global_store_dwordx2 v[126:127], v[30:31], off offset:2560
	global_load_dwordx4 v[30:33], v[102:103], off
	v_pk_mul_f32 v[38:39], v[42:43], v[128:129] op_sel_hi:[1,0]
	v_pk_mul_f32 v[40:41], v[44:45], v[128:129] op_sel_hi:[1,0]
	s_waitcnt vmcnt(0)
	v_pk_mul_f32 v[30:31], v[38:39], v[30:31]
	v_pk_mul_f32 v[32:33], v[40:41], v[32:33]
	v_cvt_pk_bf16_f32 v30, v30, v31
	v_cvt_pk_bf16_f32 v31, v32, v33
	global_store_dwordx2 v[126:127], v[30:31], off offset:3072
	global_load_dwordx4 v[30:33], v[104:105], off
	s_waitcnt vmcnt(0)
	v_pk_mul_f32 v[30:31], v[34:35], v[30:31]
	v_pk_mul_f32 v[32:33], v[36:37], v[32:33]
	v_cvt_pk_bf16_f32 v30, v30, v31
	v_cvt_pk_bf16_f32 v31, v32, v33
	global_store_dwordx2 v[126:127], v[30:31], off offset:3584
	global_load_dwordx4 v[30:33], v[106:107], off
	s_waitcnt vmcnt(0)
	v_pk_mul_f32 v[26:27], v[26:27], v[30:31]
	v_pk_mul_f32 v[28:29], v[28:29], v[32:33]
	v_cvt_pk_bf16_f32 v26, v26, v27
	v_cvt_pk_bf16_f32 v27, v28, v29
	global_store_dwordx2 v[136:137], v[26:27], off
	global_load_dwordx4 v[26:29], v[108:109], off
	s_waitcnt vmcnt(0)
	v_pk_mul_f32 v[22:23], v[22:23], v[26:27]
	v_pk_mul_f32 v[24:25], v[24:25], v[28:29]
	v_cvt_pk_bf16_f32 v22, v22, v23
	v_cvt_pk_bf16_f32 v23, v24, v25
	global_store_dwordx2 v[136:137], v[22:23], off offset:512
	global_load_dwordx4 v[22:25], v[110:111], off
	s_waitcnt vmcnt(0)
	v_pk_mul_f32 v[18:19], v[18:19], v[22:23]
	v_pk_mul_f32 v[20:21], v[20:21], v[24:25]
	v_cvt_pk_bf16_f32 v18, v18, v19
	v_cvt_pk_bf16_f32 v19, v20, v21
	global_store_dwordx2 v[136:137], v[18:19], off offset:1024
	global_load_dwordx4 v[18:21], v[112:113], off
	s_waitcnt vmcnt(0)
	v_pk_mul_f32 v[14:15], v[14:15], v[18:19]
	v_pk_mul_f32 v[16:17], v[16:17], v[20:21]
	v_cvt_pk_bf16_f32 v14, v14, v15
	v_cvt_pk_bf16_f32 v15, v16, v17
	global_store_dwordx2 v[136:137], v[14:15], off offset:1536
	global_load_dwordx4 v[14:17], v[114:115], off
	s_waitcnt vmcnt(0)
	v_pk_mul_f32 v[10:11], v[10:11], v[14:15]
	v_pk_mul_f32 v[12:13], v[12:13], v[16:17]
	v_cvt_pk_bf16_f32 v10, v10, v11
	v_cvt_pk_bf16_f32 v11, v12, v13
	global_store_dwordx2 v[136:137], v[10:11], off offset:2048
	global_load_dwordx4 v[10:13], v[116:117], off
	s_waitcnt vmcnt(0)
	v_pk_mul_f32 v[2:3], v[2:3], v[10:11]
	v_pk_mul_f32 v[4:5], v[4:5], v[12:13]
	v_cvt_pk_bf16_f32 v2, v2, v3
	v_cvt_pk_bf16_f32 v3, v4, v5
	global_store_dwordx2 v[136:137], v[2:3], off offset:2560
	global_load_dwordx4 v[2:5], v[118:119], off
	s_waitcnt vmcnt(0)
	v_pk_mul_f32 v[2:3], v[6:7], v[2:3]
	v_pk_mul_f32 v[4:5], v[8:9], v[4:5]
	v_cvt_pk_bf16_f32 v2, v2, v3
	v_cvt_pk_bf16_f32 v3, v4, v5
	global_store_dwordx2 v[136:137], v[2:3], off offset:3072
	global_load_dwordx4 v[2:5], v[120:121], off
	v_pk_mul_f32 v[6:7], v[62:63], v[128:129] op_sel_hi:[1,0]
	v_pk_mul_f32 v[8:9], v[64:65], v[128:129] op_sel_hi:[1,0]
	s_waitcnt vmcnt(0)
	v_pk_mul_f32 v[2:3], v[6:7], v[2:3]
	v_pk_mul_f32 v[4:5], v[8:9], v[4:5]
	v_cvt_pk_bf16_f32 v2, v2, v3
	v_cvt_pk_bf16_f32 v3, v4, v5
	global_store_dwordx2 v[136:137], v[2:3], off offset:3584
	s_cbranch_scc0 .LBB0_1566
.LBB0_1558:
	s_cmpk_gt_i32 s14, 0x1fff
	s_cselect_b64 s[20:21], -1, 0
	s_cmpk_lt_i32 s14, 0x2000
	s_cselect_b64 s[24:25], -1, 0
	s_or_b64 s[38:39], s[20:21], s[18:19]
	s_mov_b64 s[50:51], -1
	s_and_b64 vcc, exec, s[38:39]
	v_lshl_add_u64 v[126:127], s[30:31], 0, v[122:123]
	s_cbranch_vccnz .LBB0_1562
	s_mov_b32 s90, s14
	s_mov_b32 s91, 0
	s_lshl_b64 s[90:91], s[90:91], 14
	s_add_u32 s90, s4, s90
	s_addc_u32 s91, s5, s91
	global_load_dwordx4 v[202:205], v66, s[90:91]
	global_load_dwordx4 v[206:209], v66, s[90:91] offset:1024
	global_load_dwordx4 v[210:213], v66, s[90:91] offset:2048
	global_load_dwordx4 v[214:217], v66, s[90:91] offset:3072
	s_add_u32 s90, s90, 0x1000
	s_addc_u32 s91, s91, 0
	global_load_dwordx4 v[218:221], v66, s[90:91]
	global_load_dwordx4 v[222:225], v66, s[90:91] offset:1024
	global_load_dwordx4 v[226:229], v66, s[90:91] offset:2048
	global_load_dwordx4 v[230:233], v66, s[90:91] offset:3072
	s_add_u32 s90, s90, 0x1000
	s_addc_u32 s91, s91, 0
	global_load_dwordx4 v[234:237], v66, s[90:91]
	global_load_dwordx4 v[238:241], v66, s[90:91] offset:1024
	global_load_dwordx4 v[182:185], v66, s[90:91] offset:2048
	global_load_dwordx4 v[186:189], v66, s[90:91] offset:3072
	s_add_u32 s90, s90, 0x1000
	s_addc_u32 s91, s91, 0
	global_load_dwordx4 v[190:193], v66, s[90:91]
	global_load_dwordx4 v[194:197], v66, s[90:91] offset:1024
	global_load_dwordx4 v[244:247], v66, s[90:91] offset:2048
	global_load_dwordx4 v[248:251], v66, s[90:91] offset:3072
	v_add_co_u32_e32 v2, vcc, s45, v126
	s_nop 1
	v_addc_co_u32_e32 v3, vcc, 0, v127, vcc
	v_add_co_u32_e32 v14, vcc, 0x25500000, v126
	global_load_dwordx2 v[4:5], v[2:3], off
	global_load_dwordx2 v[6:7], v[2:3], off offset:512
	global_load_dwordx2 v[8:9], v[2:3], off offset:1024
	global_load_dwordx2 v[10:11], v[2:3], off offset:1536
	global_load_dwordx2 v[12:13], v[2:3], off offset:2048
	global_load_dwordx2 v[30:31], v[2:3], off offset:2560
	v_addc_co_u32_e32 v15, vcc, 0, v127, vcc
	global_load_dwordx2 v[62:63], v[2:3], off offset:3072
	global_load_dwordx2 v[32:33], v[14:15], off
	global_load_dwordx2 v[34:35], v[14:15], off offset:512
	global_load_dwordx2 v[36:37], v[14:15], off offset:1024
	global_load_dwordx2 v[38:39], v[14:15], off offset:1536
	global_load_dwordx2 v[40:41], v[14:15], off offset:2048
	global_load_dwordx2 v[42:43], v[14:15], off offset:2560
	global_load_dwordx2 v[44:45], v[14:15], off offset:3072
	global_load_dwordx2 v[64:65], v[14:15], off offset:3584
	global_load_dwordx2 v[128:129], v[2:3], off offset:3584
	s_waitcnt vmcnt(15)
	v_lshlrev_b32_e32 v26, 16, v4
	v_and_b32_e32 v27, 0xffff0000, v4
	v_lshlrev_b32_e32 v28, 16, v5
	v_and_b32_e32 v29, 0xffff0000, v5
	s_waitcnt vmcnt(14)
	v_lshlrev_b32_e32 v22, 16, v6
	v_and_b32_e32 v23, 0xffff0000, v6
	v_lshlrev_b32_e32 v24, 16, v7
	v_and_b32_e32 v25, 0xffff0000, v7
	s_waitcnt vmcnt(13)
	v_lshlrev_b32_e32 v18, 16, v8
	v_and_b32_e32 v19, 0xffff0000, v8
	v_lshlrev_b32_e32 v20, 16, v9
	v_and_b32_e32 v21, 0xffff0000, v9
	s_waitcnt vmcnt(12)
	v_lshlrev_b32_e32 v14, 16, v10
	v_and_b32_e32 v15, 0xffff0000, v10
	v_lshlrev_b32_e32 v16, 16, v11
	v_and_b32_e32 v17, 0xffff0000, v11
	s_waitcnt vmcnt(11)
	v_lshlrev_b32_e32 v10, 16, v12
	v_and_b32_e32 v11, 0xffff0000, v12
	v_lshlrev_b32_e32 v12, 16, v13
	v_and_b32_e32 v13, 0xffff0000, v13
	s_waitcnt vmcnt(10)
	v_lshlrev_b32_e32 v2, 16, v30
	v_and_b32_e32 v3, 0xffff0000, v30
	v_lshlrev_b32_e32 v4, 16, v31
	v_and_b32_e32 v5, 0xffff0000, v31
	s_waitcnt vmcnt(9)
	v_lshlrev_b32_e32 v6, 16, v62
	v_and_b32_e32 v7, 0xffff0000, v62
	s_waitcnt vmcnt(8)
	v_lshlrev_b32_e32 v50, 16, v32
	v_and_b32_e32 v51, 0xffff0000, v32
	v_lshlrev_b32_e32 v52, 16, v33
	v_and_b32_e32 v53, 0xffff0000, v33
	s_waitcnt vmcnt(7)
	v_lshlrev_b32_e32 v58, 16, v34
	v_and_b32_e32 v59, 0xffff0000, v34
	v_lshlrev_b32_e32 v60, 16, v35
	v_and_b32_e32 v61, 0xffff0000, v35
	s_waitcnt vmcnt(6)
	v_lshlrev_b32_e32 v54, 16, v36
	v_and_b32_e32 v55, 0xffff0000, v36
	v_lshlrev_b32_e32 v56, 16, v37
	v_and_b32_e32 v57, 0xffff0000, v37
	s_waitcnt vmcnt(5)
	v_lshlrev_b32_e32 v46, 16, v38
	v_and_b32_e32 v47, 0xffff0000, v38
	v_lshlrev_b32_e32 v48, 16, v39
	v_and_b32_e32 v49, 0xffff0000, v39
	s_waitcnt vmcnt(4)
	v_lshlrev_b32_e32 v30, 16, v40
	v_and_b32_e32 v31, 0xffff0000, v40
	v_lshlrev_b32_e32 v32, 16, v41
	v_and_b32_e32 v33, 0xffff0000, v41
	s_waitcnt vmcnt(3)
	v_lshlrev_b32_e32 v38, 16, v42
	v_and_b32_e32 v39, 0xffff0000, v42
	v_lshlrev_b32_e32 v40, 16, v43
	v_and_b32_e32 v41, 0xffff0000, v43
	s_waitcnt vmcnt(2)
	v_lshlrev_b32_e32 v42, 16, v44
	v_and_b32_e32 v43, 0xffff0000, v44
	v_lshlrev_b32_e32 v44, 16, v45
	v_and_b32_e32 v45, 0xffff0000, v45
	s_waitcnt vmcnt(1)
	v_lshlrev_b32_e32 v34, 16, v64
	v_and_b32_e32 v35, 0xffff0000, v64
	v_lshlrev_b32_e32 v36, 16, v65
	v_and_b32_e32 v37, 0xffff0000, v65
	v_lshlrev_b32_e32 v8, 16, v63
	v_and_b32_e32 v9, 0xffff0000, v63
	s_waitcnt vmcnt(0)
	v_lshlrev_b32_e32 v62, 16, v128
	v_and_b32_e32 v63, 0xffff0000, v128
	v_lshlrev_b32_e32 v64, 16, v129
	v_and_b32_e32 v65, 0xffff0000, v129
	s_cbranch_execz .LBB0_1563

.LBB0_1565:
	s_ashr_i32 s25, s24, 31
	s_lshl_b64 s[38:39], s[24:25], 14
	v_lshl_add_u64 v[128:129], v[68:69], 0, s[38:39]
	s_mov_b64 s[74:75], 0x1000
	s_mov_b64 s[76:77], 0x3000
	s_mov_b64 s[78:79], 0x1000000
	s_add_u32 s90, s6, s38
	s_addc_u32 s91, s7, s39
	v_lshl_add_u64 v[198:199], v[128:129], 0, s[74:75]
	v_lshl_add_u64 v[252:253], v[128:129], 0, s[76:77]
	global_load_dwordx4 v[202:205], v[198:199], off offset:-4096
	global_load_dwordx4 v[206:209], v[198:199], off offset:-3072
	global_load_dwordx4 v[210:213], v[198:199], off offset:-2048
	global_load_dwordx4 v[214:217], v[198:199], off offset:-1024
	global_load_dwordx4 v[218:221], v[198:199], off
	global_load_dwordx4 v[222:225], v[198:199], off offset:1024
	global_load_dwordx4 v[226:229], v[198:199], off offset:2048
	global_load_dwordx4 v[230:233], v[198:199], off offset:3072
	global_load_dwordx4 v[234:237], v[252:253], off offset:-4096
	global_load_dwordx4 v[238:241], v[252:253], off offset:-3072
	global_load_dwordx4 v[182:185], v[252:253], off offset:-2048
	global_load_dwordx4 v[186:189], v[252:253], off offset:-1024
	global_load_dwordx4 v[190:193], v[252:253], off
	global_load_dwordx4 v[194:197], v[252:253], off offset:1024
	global_load_dwordx4 v[244:247], v[252:253], off offset:2048
	global_load_dwordx4 v[248:251], v[252:253], off offset:3072
	v_lshl_add_u64 v[198:199], v[198:199], 0, s[78:79]
	v_lshl_add_u64 v[252:253], v[252:253], 0, s[78:79]
	s_waitcnt vmcnt(15)
	v_pk_add_f32 v[50:51], v[202:203], v[50:51]
	v_pk_add_f32 v[52:53], v[204:205], v[52:53]
	global_load_dwordx4 v[202:205], v[198:199], off offset:-4096
	s_waitcnt vmcnt(15)
	v_pk_add_f32 v[58:59], v[206:207], v[58:59]
	v_pk_add_f32 v[60:61], v[208:209], v[60:61]
	global_load_dwordx4 v[206:209], v[198:199], off offset:-3072
	s_waitcnt vmcnt(15)
	v_pk_add_f32 v[54:55], v[210:211], v[54:55]
	v_pk_add_f32 v[56:57], v[212:213], v[56:57]
	global_load_dwordx4 v[210:213], v[198:199], off offset:-2048
	s_waitcnt vmcnt(15)
	v_pk_add_f32 v[46:47], v[214:215], v[46:47]
	v_pk_add_f32 v[48:49], v[216:217], v[48:49]
	global_load_dwordx4 v[214:217], v[198:199], off offset:-1024
	s_waitcnt vmcnt(15)
	v_pk_add_f32 v[30:31], v[218:219], v[30:31]
	v_pk_add_f32 v[32:33], v[220:221], v[32:33]
	global_load_dwordx4 v[218:221], v[198:199], off
	s_waitcnt vmcnt(15)
	v_pk_add_f32 v[38:39], v[222:223], v[38:39]
	v_pk_add_f32 v[40:41], v[224:225], v[40:41]
	global_load_dwordx4 v[222:225], v[198:199], off offset:1024
	s_waitcnt vmcnt(15)
	v_pk_add_f32 v[42:43], v[226:227], v[42:43]
	v_pk_add_f32 v[44:45], v[228:229], v[44:45]
	global_load_dwordx4 v[226:229], v[198:199], off offset:2048
	s_waitcnt vmcnt(15)
	v_pk_add_f32 v[34:35], v[230:231], v[34:35]
	v_pk_add_f32 v[36:37], v[232:233], v[36:37]
	global_load_dwordx4 v[230:233], v[198:199], off offset:3072
	s_waitcnt vmcnt(15)
	v_pk_add_f32 v[26:27], v[234:235], v[26:27]
	v_pk_add_f32 v[28:29], v[236:237], v[28:29]
	global_load_dwordx4 v[234:237], v[252:253], off offset:-4096
	s_waitcnt vmcnt(15)
	v_pk_add_f32 v[22:23], v[238:239], v[22:23]
	v_pk_add_f32 v[24:25], v[240:241], v[24:25]
	global_load_dwordx4 v[238:241], v[252:253], off offset:-3072
	s_waitcnt vmcnt(15)
	v_pk_add_f32 v[18:19], v[182:183], v[18:19]
	v_pk_add_f32 v[20:21], v[184:185], v[20:21]
	global_load_dwordx4 v[182:185], v[252:253], off offset:-2048
	s_waitcnt vmcnt(15)
	v_pk_add_f32 v[14:15], v[186:187], v[14:15]
	v_pk_add_f32 v[16:17], v[188:189], v[16:17]
	global_load_dwordx4 v[186:189], v[252:253], off offset:-1024
	s_waitcnt vmcnt(15)
	v_pk_add_f32 v[10:11], v[190:191], v[10:11]
	v_pk_add_f32 v[12:13], v[192:193], v[12:13]
	global_load_dwordx4 v[190:193], v[252:253], off
	s_waitcnt vmcnt(15)
	v_pk_add_f32 v[2:3], v[194:195], v[2:3]
	v_pk_add_f32 v[4:5], v[196:197], v[4:5]
	global_load_dwordx4 v[194:197], v[252:253], off offset:1024
	s_waitcnt vmcnt(15)
	v_pk_add_f32 v[6:7], v[244:245], v[6:7]
	v_pk_add_f32 v[8:9], v[246:247], v[8:9]
	global_load_dwordx4 v[244:247], v[252:253], off offset:2048
	s_waitcnt vmcnt(15)
	v_pk_add_f32 v[62:63], v[248:249], v[62:63]
	v_pk_add_f32 v[64:65], v[250:251], v[64:65]
	global_load_dwordx4 v[248:251], v[252:253], off offset:3072
	v_lshl_add_u64 v[198:199], v[198:199], 0, s[78:79]
	v_lshl_add_u64 v[252:253], v[252:253], 0, s[78:79]
	s_waitcnt vmcnt(15)
	v_pk_add_f32 v[50:51], v[202:203], v[50:51]
	v_pk_add_f32 v[52:53], v[204:205], v[52:53]
	global_load_dwordx4 v[202:205], v[198:199], off offset:-4096
	s_waitcnt vmcnt(15)
	v_pk_add_f32 v[58:59], v[206:207], v[58:59]
	v_pk_add_f32 v[60:61], v[208:209], v[60:61]
	global_load_dwordx4 v[206:209], v[198:199], off offset:-3072
	s_waitcnt vmcnt(15)
	v_pk_add_f32 v[54:55], v[210:211], v[54:55]
	v_pk_add_f32 v[56:57], v[212:213], v[56:57]
	global_load_dwordx4 v[210:213], v[198:199], off offset:-2048
	s_waitcnt vmcnt(15)
	v_pk_add_f32 v[46:47], v[214:215], v[46:47]
	v_pk_add_f32 v[48:49], v[216:217], v[48:49]
	global_load_dwordx4 v[214:217], v[198:199], off offset:-1024
	s_waitcnt vmcnt(15)
	v_pk_add_f32 v[30:31], v[218:219], v[30:31]
	v_pk_add_f32 v[32:33], v[220:221], v[32:33]
	global_load_dwordx4 v[218:221], v[198:199], off
	s_waitcnt vmcnt(15)
	v_pk_add_f32 v[38:39], v[222:223], v[38:39]
	v_pk_add_f32 v[40:41], v[224:225], v[40:41]
	global_load_dwordx4 v[222:225], v[198:199], off offset:1024
	s_waitcnt vmcnt(15)
	v_pk_add_f32 v[42:43], v[226:227], v[42:43]
	v_pk_add_f32 v[44:45], v[228:229], v[44:45]
	global_load_dwordx4 v[226:229], v[198:199], off offset:2048
	s_waitcnt vmcnt(15)
	v_pk_add_f32 v[34:35], v[230:231], v[34:35]
	v_pk_add_f32 v[36:37], v[232:233], v[36:37]
	global_load_dwordx4 v[230:233], v[198:199], off offset:3072
	s_waitcnt vmcnt(15)
	v_pk_add_f32 v[26:27], v[234:235], v[26:27]
	v_pk_add_f32 v[28:29], v[236:237], v[28:29]
	global_load_dwordx4 v[234:237], v[252:253], off offset:-4096
	s_waitcnt vmcnt(15)
	v_pk_add_f32 v[22:23], v[238:239], v[22:23]
	v_pk_add_f32 v[24:25], v[240:241], v[24:25]
	global_load_dwordx4 v[238:241], v[252:253], off offset:-3072
	s_waitcnt vmcnt(15)
	v_pk_add_f32 v[18:19], v[182:183], v[18:19]
	v_pk_add_f32 v[20:21], v[184:185], v[20:21]
	global_load_dwordx4 v[182:185], v[252:253], off offset:-2048
	s_waitcnt vmcnt(15)
	v_pk_add_f32 v[14:15], v[186:187], v[14:15]
	v_pk_add_f32 v[16:17], v[188:189], v[16:17]
	global_load_dwordx4 v[186:189], v[252:253], off offset:-1024
	s_waitcnt vmcnt(15)
	v_pk_add_f32 v[10:11], v[190:191], v[10:11]
	v_pk_add_f32 v[12:13], v[192:193], v[12:13]
	global_load_dwordx4 v[190:193], v[252:253], off
	s_waitcnt vmcnt(15)
	v_pk_add_f32 v[2:3], v[194:195], v[2:3]
	v_pk_add_f32 v[4:5], v[196:197], v[4:5]
	global_load_dwordx4 v[194:197], v[252:253], off offset:1024
	s_waitcnt vmcnt(15)
	v_pk_add_f32 v[6:7], v[244:245], v[6:7]
	v_pk_add_f32 v[8:9], v[246:247], v[8:9]
	global_load_dwordx4 v[244:247], v[252:253], off offset:2048
	s_waitcnt vmcnt(15)
	v_pk_add_f32 v[62:63], v[248:249], v[62:63]
	v_pk_add_f32 v[64:65], v[250:251], v[64:65]
	global_load_dwordx4 v[248:251], v[252:253], off offset:3072
	s_waitcnt vmcnt(15)
	v_pk_add_f32 v[50:51], v[202:203], v[50:51]
	v_pk_add_f32 v[52:53], v[204:205], v[52:53]
	global_load_dwordx4 v[202:205], v66, s[90:91]
	s_waitcnt vmcnt(15)
	v_pk_add_f32 v[58:59], v[206:207], v[58:59]
	v_pk_add_f32 v[60:61], v[208:209], v[60:61]
	global_load_dwordx4 v[206:209], v66, s[90:91] offset:1024
	s_waitcnt vmcnt(15)
	v_pk_add_f32 v[54:55], v[210:211], v[54:55]
	v_pk_add_f32 v[56:57], v[212:213], v[56:57]
	global_load_dwordx4 v[210:213], v66, s[90:91] offset:2048
	s_waitcnt vmcnt(15)
	v_pk_add_f32 v[46:47], v[214:215], v[46:47]
	v_pk_add_f32 v[48:49], v[216:217], v[48:49]
	global_load_dwordx4 v[214:217], v66, s[90:91] offset:3072
	s_add_u32 s90, s90, 0x1000
	s_addc_u32 s91, s91, 0
	s_waitcnt vmcnt(15)
	v_pk_add_f32 v[30:31], v[218:219], v[30:31]
	v_pk_add_f32 v[32:33], v[220:221], v[32:33]
	global_load_dwordx4 v[218:221], v66, s[90:91]
	s_waitcnt vmcnt(15)
	v_pk_add_f32 v[38:39], v[222:223], v[38:39]
	v_pk_add_f32 v[40:41], v[224:225], v[40:41]
	global_load_dwordx4 v[222:225], v66, s[90:91] offset:1024
	s_waitcnt vmcnt(15)
	v_pk_add_f32 v[42:43], v[226:227], v[42:43]
	v_pk_add_f32 v[44:45], v[228:229], v[44:45]
	global_load_dwordx4 v[226:229], v66, s[90:91] offset:2048
	s_waitcnt vmcnt(15)
	v_pk_add_f32 v[34:35], v[230:231], v[34:35]
	v_pk_add_f32 v[36:37], v[232:233], v[36:37]
	global_load_dwordx4 v[230:233], v66, s[90:91] offset:3072
	s_add_u32 s90, s90, 0x1000
	s_addc_u32 s91, s91, 0
	s_waitcnt vmcnt(15)
	v_pk_add_f32 v[26:27], v[234:235], v[26:27]
	v_pk_add_f32 v[28:29], v[236:237], v[28:29]
	global_load_dwordx4 v[234:237], v66, s[90:91]
	s_waitcnt vmcnt(15)
	v_pk_add_f32 v[22:23], v[238:239], v[22:23]
	v_pk_add_f32 v[24:25], v[240:241], v[24:25]
	global_load_dwordx4 v[238:241], v66, s[90:91] offset:1024
	s_waitcnt vmcnt(15)
	v_pk_add_f32 v[18:19], v[182:183], v[18:19]
	v_pk_add_f32 v[20:21], v[184:185], v[20:21]
	global_load_dwordx4 v[182:185], v66, s[90:91] offset:2048
	s_waitcnt vmcnt(15)
	v_pk_add_f32 v[14:15], v[186:187], v[14:15]
	v_pk_add_f32 v[16:17], v[188:189], v[16:17]
	global_load_dwordx4 v[186:189], v66, s[90:91] offset:3072
	s_add_u32 s90, s90, 0x1000
	s_addc_u32 s91, s91, 0
	s_waitcnt vmcnt(15)
	v_pk_add_f32 v[10:11], v[190:191], v[10:11]
	v_pk_add_f32 v[12:13], v[192:193], v[12:13]
	global_load_dwordx4 v[190:193], v66, s[90:91]
	s_waitcnt vmcnt(15)
	v_pk_add_f32 v[2:3], v[194:195], v[2:3]
	v_pk_add_f32 v[4:5], v[196:197], v[4:5]
	global_load_dwordx4 v[194:197], v66, s[90:91] offset:1024
	s_waitcnt vmcnt(15)
	v_pk_add_f32 v[6:7], v[244:245], v[6:7]
	v_pk_add_f32 v[8:9], v[246:247], v[8:9]
	global_load_dwordx4 v[244:247], v66, s[90:91] offset:2048
	s_waitcnt vmcnt(15)
	v_pk_add_f32 v[62:63], v[248:249], v[62:63]
	v_pk_add_f32 v[64:65], v[250:251], v[64:65]
	global_load_dwordx4 v[248:251], v66, s[90:91] offset:3072
	s_branch .LBB0_1557

.LBB0_2065:
	s_mov_b64 s[74:75], 0x1000
	s_mov_b64 s[76:77], 0x2000
	v_lshl_add_u64 v[198:199], s[28:29], 0, v[130:131]
	v_lshl_add_u64 v[198:199], v[198:199], 0, s[74:75]
	global_load_dwordx4 v[202:205], v[198:199], off offset:-4096
	global_load_dwordx4 v[206:209], v[198:199], off offset:-3072
	global_load_dwordx4 v[210:213], v[198:199], off offset:-2048
	global_load_dwordx4 v[214:217], v[198:199], off offset:-1024
	global_load_dwordx4 v[218:221], v[198:199], off
	global_load_dwordx4 v[222:225], v[198:199], off offset:1024
	global_load_dwordx4 v[226:229], v[198:199], off offset:2048
	global_load_dwordx4 v[230:233], v[198:199], off offset:3072
	v_lshl_add_u64 v[198:199], v[198:199], 0, s[76:77]
	global_load_dwordx4 v[234:237], v[198:199], off offset:-4096
	global_load_dwordx4 v[238:241], v[198:199], off offset:-3072
	global_load_dwordx4 v[186:189], v[198:199], off offset:-2048
	global_load_dwordx4 v[190:193], v[198:199], off offset:-1024
	global_load_dwordx4 v[194:197], v[198:199], off
	global_load_dwordx4 v[244:247], v[198:199], off offset:1024
	global_load_dwordx4 v[248:251], v[198:199], off offset:2048
	global_load_dwordx4 v[252:255], v[198:199], off offset:3072
	s_cmpk_lt_i32 s42, 0x2000
	s_cselect_b64 s[12:13], -1, 0
	s_cmpk_gt_i32 s42, 0x1fff
	s_cselect_b64 s[14:15], -1, 0
	s_or_b64 s[38:39], s[14:15], s[0:1]
	s_mov_b64 s[14:15], -1
	s_and_b64 vcc, exec, s[38:39]
	v_lshl_add_u64 v[136:137], s[30:31], 0, v[134:135]
	s_cbranch_vccnz .LBB0_2069
	v_add_co_u32_e32 v2, vcc, s17, v136
	s_nop 1
	v_addc_co_u32_e32 v3, vcc, 0, v137, vcc
	v_add_co_u32_e32 v16, vcc, 0x25500000, v136
	global_load_dwordx2 v[4:5], v[2:3], off
	global_load_dwordx2 v[6:7], v[2:3], off offset:512
	global_load_dwordx2 v[8:9], v[2:3], off offset:1024
	global_load_dwordx2 v[10:11], v[2:3], off offset:1536
	global_load_dwordx2 v[12:13], v[2:3], off offset:2048
	global_load_dwordx2 v[14:15], v[2:3], off offset:2560
	v_addc_co_u32_e32 v17, vcc, 0, v137, vcc
	global_load_dwordx2 v[54:55], v[2:3], off offset:3072
	global_load_dwordx2 v[18:19], v[16:17], off
	global_load_dwordx2 v[20:21], v[16:17], off offset:512
	global_load_dwordx2 v[34:35], v[16:17], off offset:1024
	global_load_dwordx2 v[36:37], v[16:17], off offset:1536
	global_load_dwordx2 v[38:39], v[16:17], off offset:2048
	global_load_dwordx2 v[40:41], v[16:17], off offset:2560
	global_load_dwordx2 v[56:57], v[16:17], off offset:3072
	global_load_dwordx2 v[66:67], v[16:17], off offset:3584
	global_load_dwordx2 v[68:69], v[2:3], off offset:3584
	s_waitcnt vmcnt(15)
	v_lshlrev_b32_e32 v22, 16, v4
	v_and_b32_e32 v23, 0xffff0000, v4
	v_lshlrev_b32_e32 v24, 16, v5
	v_and_b32_e32 v25, 0xffff0000, v5
	s_waitcnt vmcnt(14)
	v_lshlrev_b32_e32 v30, 16, v6
	v_and_b32_e32 v31, 0xffff0000, v6
	v_lshlrev_b32_e32 v32, 16, v7
	v_and_b32_e32 v33, 0xffff0000, v7
	s_waitcnt vmcnt(13)
	v_lshlrev_b32_e32 v26, 16, v8
	v_and_b32_e32 v27, 0xffff0000, v8
	v_lshlrev_b32_e32 v28, 16, v9
	v_and_b32_e32 v29, 0xffff0000, v9
	s_waitcnt vmcnt(12)
	v_lshlrev_b32_e32 v42, 16, v10
	v_and_b32_e32 v43, 0xffff0000, v10
	v_lshlrev_b32_e32 v44, 16, v11
	v_and_b32_e32 v45, 0xffff0000, v11
	s_waitcnt vmcnt(11)
	v_lshlrev_b32_e32 v2, 16, v12
	v_and_b32_e32 v3, 0xffff0000, v12
	v_lshlrev_b32_e32 v4, 16, v13
	v_and_b32_e32 v5, 0xffff0000, v13
	s_waitcnt vmcnt(10)
	v_lshlrev_b32_e32 v10, 16, v14
	v_and_b32_e32 v11, 0xffff0000, v14
	v_lshlrev_b32_e32 v12, 16, v15
	v_and_b32_e32 v13, 0xffff0000, v15
	s_waitcnt vmcnt(9)
	v_lshlrev_b32_e32 v14, 16, v54
	v_and_b32_e32 v15, 0xffff0000, v54
	s_waitcnt vmcnt(8)
	v_lshlrev_b32_e32 v58, 16, v18
	v_and_b32_e32 v59, 0xffff0000, v18
	v_lshlrev_b32_e32 v60, 16, v19
	v_and_b32_e32 v61, 0xffff0000, v19
	s_waitcnt vmcnt(7)
	v_lshlrev_b32_e32 v62, 16, v20
	v_and_b32_e32 v63, 0xffff0000, v20
	v_lshlrev_b32_e32 v64, 16, v21
	v_and_b32_e32 v65, 0xffff0000, v21
	s_waitcnt vmcnt(6)
	v_lshlrev_b32_e32 v50, 16, v34
	v_and_b32_e32 v51, 0xffff0000, v34
	v_lshlrev_b32_e32 v52, 16, v35
	v_and_b32_e32 v53, 0xffff0000, v35
	s_waitcnt vmcnt(5)
	v_lshlrev_b32_e32 v46, 16, v36
	v_and_b32_e32 v47, 0xffff0000, v36
	v_lshlrev_b32_e32 v48, 16, v37
	v_and_b32_e32 v49, 0xffff0000, v37
	s_waitcnt vmcnt(4)
	v_lshlrev_b32_e32 v6, 16, v38
	v_and_b32_e32 v7, 0xffff0000, v38
	v_lshlrev_b32_e32 v8, 16, v39
	v_and_b32_e32 v9, 0xffff0000, v39
	s_waitcnt vmcnt(3)
	v_lshlrev_b32_e32 v18, 16, v40
	v_and_b32_e32 v19, 0xffff0000, v40
	v_lshlrev_b32_e32 v20, 16, v41
	v_and_b32_e32 v21, 0xffff0000, v41
	s_waitcnt vmcnt(2)
	v_lshlrev_b32_e32 v34, 16, v56
	v_and_b32_e32 v35, 0xffff0000, v56
	v_lshlrev_b32_e32 v36, 16, v57
	v_and_b32_e32 v37, 0xffff0000, v57
	s_waitcnt vmcnt(1)
	v_lshlrev_b32_e32 v38, 16, v66
	v_and_b32_e32 v39, 0xffff0000, v66
	v_lshlrev_b32_e32 v40, 16, v67
	v_and_b32_e32 v41, 0xffff0000, v67
	v_lshlrev_b32_e32 v16, 16, v55
	v_and_b32_e32 v17, 0xffff0000, v55
	s_waitcnt vmcnt(0)
	v_lshlrev_b32_e32 v54, 16, v68
	v_and_b32_e32 v55, 0xffff0000, v68
	v_lshlrev_b32_e32 v56, 16, v69
	v_and_b32_e32 v57, 0xffff0000, v69
	s_cbranch_execz .LBB0_2070

.LBB0_2072:
	s_add_i32 s12, s42, 0xffffe000
	s_ashr_i32 s13, s12, 31
	s_lshl_b64 s[12:13], s[12:13], 14
	v_lshl_add_u64 v[66:67], v[78:79], 0, s[12:13]
	s_mov_b64 s[74:75], 0x1000
	s_mov_b64 s[76:77], 0x2000
	s_mov_b64 s[78:79], 0xffe000
	v_lshl_add_u64 v[198:199], v[66:67], 0, s[74:75]
	global_load_dwordx4 v[202:205], v[198:199], off offset:-4096
	global_load_dwordx4 v[206:209], v[198:199], off offset:-3072
	global_load_dwordx4 v[210:213], v[198:199], off offset:-2048
	global_load_dwordx4 v[214:217], v[198:199], off offset:-1024
	global_load_dwordx4 v[218:221], v[198:199], off
	global_load_dwordx4 v[222:225], v[198:199], off offset:1024
	global_load_dwordx4 v[226:229], v[198:199], off offset:2048
	global_load_dwordx4 v[230:233], v[198:199], off offset:3072
	v_lshl_add_u64 v[198:199], v[198:199], 0, s[76:77]
	global_load_dwordx4 v[234:237], v[198:199], off offset:-4096
	global_load_dwordx4 v[238:241], v[198:199], off offset:-3072
	global_load_dwordx4 v[186:189], v[198:199], off offset:-2048
	global_load_dwordx4 v[190:193], v[198:199], off offset:-1024
	global_load_dwordx4 v[194:197], v[198:199], off
	global_load_dwordx4 v[244:247], v[198:199], off offset:1024
	global_load_dwordx4 v[248:251], v[198:199], off offset:2048
	global_load_dwordx4 v[252:255], v[198:199], off offset:3072
	s_waitcnt vmcnt(15)
	v_pk_add_f32 v[58:59], v[202:203], v[58:59]
	v_pk_add_f32 v[60:61], v[204:205], v[60:61]
	v_lshl_add_u64 v[198:199], v[198:199], 0, s[78:79]
	global_load_dwordx4 v[202:205], v[198:199], off offset:-4096
	s_waitcnt vmcnt(15)
	v_pk_add_f32 v[62:63], v[206:207], v[62:63]
	v_pk_add_f32 v[64:65], v[208:209], v[64:65]
	global_load_dwordx4 v[206:209], v[198:199], off offset:-3072
	s_waitcnt vmcnt(15)
	v_pk_add_f32 v[50:51], v[210:211], v[50:51]
	v_pk_add_f32 v[52:53], v[212:213], v[52:53]
	global_load_dwordx4 v[210:213], v[198:199], off offset:-2048
	s_waitcnt vmcnt(15)
	v_pk_add_f32 v[46:47], v[214:215], v[46:47]
	v_pk_add_f32 v[48:49], v[216:217], v[48:49]
	global_load_dwordx4 v[214:217], v[198:199], off offset:-1024
	s_waitcnt vmcnt(15)
	v_pk_add_f32 v[6:7], v[218:219], v[6:7]
	v_pk_add_f32 v[8:9], v[220:221], v[8:9]
	global_load_dwordx4 v[218:221], v[198:199], off
	s_waitcnt vmcnt(15)
	v_pk_add_f32 v[18:19], v[222:223], v[18:19]
	v_pk_add_f32 v[20:21], v[224:225], v[20:21]
	global_load_dwordx4 v[222:225], v[198:199], off offset:1024
	s_waitcnt vmcnt(15)
	v_pk_add_f32 v[34:35], v[226:227], v[34:35]
	v_pk_add_f32 v[36:37], v[228:229], v[36:37]
	global_load_dwordx4 v[226:229], v[198:199], off offset:2048
	s_waitcnt vmcnt(15)
	v_pk_add_f32 v[38:39], v[230:231], v[38:39]
	v_pk_add_f32 v[40:41], v[232:233], v[40:41]
	global_load_dwordx4 v[230:233], v[198:199], off offset:3072
	s_waitcnt vmcnt(15)
	v_pk_add_f32 v[22:23], v[234:235], v[22:23]
	v_pk_add_f32 v[24:25], v[236:237], v[24:25]
	v_lshl_add_u64 v[198:199], v[198:199], 0, s[76:77]
	global_load_dwordx4 v[234:237], v[198:199], off offset:-4096
	s_waitcnt vmcnt(15)
	v_pk_add_f32 v[30:31], v[238:239], v[30:31]
	v_pk_add_f32 v[32:33], v[240:241], v[32:33]
	global_load_dwordx4 v[238:241], v[198:199], off offset:-3072
	s_waitcnt vmcnt(15)
	v_pk_add_f32 v[26:27], v[186:187], v[26:27]
	v_pk_add_f32 v[28:29], v[188:189], v[28:29]
	global_load_dwordx4 v[186:189], v[198:199], off offset:-2048
	s_waitcnt vmcnt(15)
	v_pk_add_f32 v[42:43], v[190:191], v[42:43]
	v_pk_add_f32 v[44:45], v[192:193], v[44:45]
	global_load_dwordx4 v[190:193], v[198:199], off offset:-1024
	s_waitcnt vmcnt(15)
	v_pk_add_f32 v[2:3], v[194:195], v[2:3]
	v_pk_add_f32 v[4:5], v[196:197], v[4:5]
	global_load_dwordx4 v[194:197], v[198:199], off
	s_waitcnt vmcnt(15)
	v_pk_add_f32 v[10:11], v[244:245], v[10:11]
	v_pk_add_f32 v[12:13], v[246:247], v[12:13]
	global_load_dwordx4 v[244:247], v[198:199], off offset:1024
	s_waitcnt vmcnt(15)
	v_pk_add_f32 v[14:15], v[248:249], v[14:15]
	v_pk_add_f32 v[16:17], v[250:251], v[16:17]
	global_load_dwordx4 v[248:251], v[198:199], off offset:2048
	s_waitcnt vmcnt(15)
	v_pk_add_f32 v[54:55], v[252:253], v[54:55]
	v_pk_add_f32 v[56:57], v[254:255], v[56:57]
	global_load_dwordx4 v[252:255], v[198:199], off offset:3072
	s_waitcnt vmcnt(15)
	v_pk_add_f32 v[58:59], v[202:203], v[58:59]
	v_pk_add_f32 v[60:61], v[204:205], v[60:61]
	v_lshl_add_u64 v[198:199], v[198:199], 0, s[78:79]
	global_load_dwordx4 v[202:205], v[198:199], off offset:-4096
	s_waitcnt vmcnt(15)
	v_pk_add_f32 v[62:63], v[206:207], v[62:63]
	v_pk_add_f32 v[64:65], v[208:209], v[64:65]
	global_load_dwordx4 v[206:209], v[198:199], off offset:-3072
	s_waitcnt vmcnt(15)
	v_pk_add_f32 v[50:51], v[210:211], v[50:51]
	v_pk_add_f32 v[52:53], v[212:213], v[52:53]
	global_load_dwordx4 v[210:213], v[198:199], off offset:-2048
	s_waitcnt vmcnt(15)
	v_pk_add_f32 v[46:47], v[214:215], v[46:47]
	v_pk_add_f32 v[48:49], v[216:217], v[48:49]
	global_load_dwordx4 v[214:217], v[198:199], off offset:-1024
	s_waitcnt vmcnt(15)
	v_pk_add_f32 v[6:7], v[218:219], v[6:7]
	v_pk_add_f32 v[8:9], v[220:221], v[8:9]
	global_load_dwordx4 v[218:221], v[198:199], off
	s_waitcnt vmcnt(15)
	v_pk_add_f32 v[18:19], v[222:223], v[18:19]
	v_pk_add_f32 v[20:21], v[224:225], v[20:21]
	global_load_dwordx4 v[222:225], v[198:199], off offset:1024
	s_waitcnt vmcnt(15)
	v_pk_add_f32 v[34:35], v[226:227], v[34:35]
	v_pk_add_f32 v[36:37], v[228:229], v[36:37]
	global_load_dwordx4 v[226:229], v[198:199], off offset:2048
	s_waitcnt vmcnt(15)
	v_pk_add_f32 v[38:39], v[230:231], v[38:39]
	v_pk_add_f32 v[40:41], v[232:233], v[40:41]
	global_load_dwordx4 v[230:233], v[198:199], off offset:3072
	s_waitcnt vmcnt(15)
	v_pk_add_f32 v[22:23], v[234:235], v[22:23]
	v_pk_add_f32 v[24:25], v[236:237], v[24:25]
	v_lshl_add_u64 v[198:199], v[198:199], 0, s[76:77]
	global_load_dwordx4 v[234:237], v[198:199], off offset:-4096
	s_waitcnt vmcnt(15)
	v_pk_add_f32 v[30:31], v[238:239], v[30:31]
	v_pk_add_f32 v[32:33], v[240:241], v[32:33]
	global_load_dwordx4 v[238:241], v[198:199], off offset:-3072
	s_waitcnt vmcnt(15)
	v_pk_add_f32 v[26:27], v[186:187], v[26:27]
	v_pk_add_f32 v[28:29], v[188:189], v[28:29]
	global_load_dwordx4 v[186:189], v[198:199], off offset:-2048
	s_waitcnt vmcnt(15)
	v_pk_add_f32 v[42:43], v[190:191], v[42:43]
	v_pk_add_f32 v[44:45], v[192:193], v[44:45]
	global_load_dwordx4 v[190:193], v[198:199], off offset:-1024
	s_waitcnt vmcnt(15)
	v_pk_add_f32 v[2:3], v[194:195], v[2:3]
	v_pk_add_f32 v[4:5], v[196:197], v[4:5]
	global_load_dwordx4 v[194:197], v[198:199], off
	s_waitcnt vmcnt(15)
	v_pk_add_f32 v[10:11], v[244:245], v[10:11]
	v_pk_add_f32 v[12:13], v[246:247], v[12:13]
	global_load_dwordx4 v[244:247], v[198:199], off offset:1024
	s_waitcnt vmcnt(15)
	v_pk_add_f32 v[14:15], v[248:249], v[14:15]
	v_pk_add_f32 v[16:17], v[250:251], v[16:17]
	global_load_dwordx4 v[248:251], v[198:199], off offset:2048
	s_waitcnt vmcnt(15)
	v_pk_add_f32 v[54:55], v[252:253], v[54:55]
	v_pk_add_f32 v[56:57], v[254:255], v[56:57]
	global_load_dwordx4 v[252:255], v[198:199], off offset:3072
	s_waitcnt vmcnt(15)
	v_pk_add_f32 v[58:59], v[202:203], v[58:59]
	v_pk_add_f32 v[60:61], v[204:205], v[60:61]
	s_waitcnt vmcnt(14)
	v_pk_add_f32 v[62:63], v[206:207], v[62:63]
	v_pk_add_f32 v[64:65], v[208:209], v[64:65]
	s_waitcnt vmcnt(13)
	v_pk_add_f32 v[50:51], v[210:211], v[50:51]
	v_pk_add_f32 v[52:53], v[212:213], v[52:53]
	s_waitcnt vmcnt(12)
	v_pk_add_f32 v[46:47], v[214:215], v[46:47]
	v_pk_add_f32 v[48:49], v[216:217], v[48:49]
	s_waitcnt vmcnt(11)
	v_pk_add_f32 v[6:7], v[218:219], v[6:7]
	v_pk_add_f32 v[8:9], v[220:221], v[8:9]
	s_waitcnt vmcnt(10)
	v_pk_add_f32 v[18:19], v[222:223], v[18:19]
	v_pk_add_f32 v[20:21], v[224:225], v[20:21]
	s_waitcnt vmcnt(9)
	v_pk_add_f32 v[34:35], v[226:227], v[34:35]
	v_pk_add_f32 v[36:37], v[228:229], v[36:37]
	s_waitcnt vmcnt(8)
	v_pk_add_f32 v[38:39], v[230:231], v[38:39]
	v_pk_add_f32 v[40:41], v[232:233], v[40:41]
	s_waitcnt vmcnt(7)
	v_pk_add_f32 v[22:23], v[234:235], v[22:23]
	v_pk_add_f32 v[24:25], v[236:237], v[24:25]
	s_waitcnt vmcnt(6)
	v_pk_add_f32 v[30:31], v[238:239], v[30:31]
	v_pk_add_f32 v[32:33], v[240:241], v[32:33]
	s_waitcnt vmcnt(5)
	v_pk_add_f32 v[26:27], v[186:187], v[26:27]
	v_pk_add_f32 v[28:29], v[188:189], v[28:29]
	s_waitcnt vmcnt(4)
	v_pk_add_f32 v[42:43], v[190:191], v[42:43]
	v_pk_add_f32 v[44:45], v[192:193], v[44:45]
	s_waitcnt vmcnt(3)
	v_pk_add_f32 v[2:3], v[194:195], v[2:3]
	v_pk_add_f32 v[4:5], v[196:197], v[4:5]
	s_waitcnt vmcnt(2)
	v_pk_add_f32 v[10:11], v[244:245], v[10:11]
	v_pk_add_f32 v[12:13], v[246:247], v[12:13]
	s_waitcnt vmcnt(1)
	v_pk_add_f32 v[14:15], v[248:249], v[14:15]
	v_pk_add_f32 v[16:17], v[250:251], v[16:17]
	s_waitcnt vmcnt(0)
	v_pk_add_f32 v[54:55], v[252:253], v[54:55]
	v_pk_add_f32 v[56:57], v[254:255], v[56:57]
	s_branch .LBB0_2064

	.amdhsa_kernel _Z10fwd_kernel4Args
		.amdhsa_group_segment_fixed_size 0
		.amdhsa_private_segment_fixed_size 0
		.amdhsa_kernarg_size 576
		.amdhsa_user_sgpr_count 2
		.amdhsa_user_sgpr_dispatch_ptr 0
		.amdhsa_user_sgpr_queue_ptr 0
		.amdhsa_user_sgpr_kernarg_segment_ptr 1
		.amdhsa_user_sgpr_dispatch_id 0
		.amdhsa_user_sgpr_kernarg_preload_length 0
		.amdhsa_user_sgpr_kernarg_preload_offset 0
		.amdhsa_user_sgpr_private_segment_size 0
		.amdhsa_uses_dynamic_stack 0
		.amdhsa_enable_private_segment 0
		.amdhsa_system_sgpr_workgroup_id_x 1
		.amdhsa_system_sgpr_workgroup_id_y 0
		.amdhsa_system_sgpr_workgroup_id_z 0
		.amdhsa_system_sgpr_workgroup_info 0
		.amdhsa_system_vgpr_workitem_id 0
		.amdhsa_next_free_vgpr 256
		.amdhsa_next_free_sgpr 98
		.amdhsa_accum_offset 256
		.amdhsa_reserve_vcc 1
		.amdhsa_float_round_mode_32 0
		.amdhsa_float_round_mode_16_64 0
		.amdhsa_float_denorm_mode_32 3
		.amdhsa_float_denorm_mode_16_64 3
		.amdhsa_dx10_clamp 1
		.amdhsa_ieee_mode 1
		.amdhsa_fp16_overflow 0
		.amdhsa_tg_split 0
		.amdhsa_exception_fp_ieee_invalid_op 0
		.amdhsa_exception_fp_denorm_src 0
		.amdhsa_exception_fp_ieee_div_zero 0
		.amdhsa_exception_fp_ieee_overflow 0
		.amdhsa_exception_fp_ieee_underflow 0
		.amdhsa_exception_fp_ieee_inexact 0
		.amdhsa_exception_int_div_zero 0
	.end_amdhsa_kernel

amdhsa.kernels:
  - .agpr_count:     0
    .args:
      - .offset:         0
        .size:           320
        .value_kind:     by_value
      - .offset:         320
        .size:           4
        .value_kind:     hidden_block_count_x
      - .offset:         324
        .size:           4
        .value_kind:     hidden_block_count_y
      - .offset:         328
        .size:           4
        .value_kind:     hidden_block_count_z
      - .offset:         332
        .size:           2
        .value_kind:     hidden_group_size_x
      - .offset:         334
        .size:           2
        .value_kind:     hidden_group_size_y
      - .offset:         336
        .size:           2
        .value_kind:     hidden_group_size_z
      - .offset:         338
        .size:           2
        .value_kind:     hidden_remainder_x
      - .offset:         340
        .size:           2
        .value_kind:     hidden_remainder_y
      - .offset:         342
        .size:           2
        .value_kind:     hidden_remainder_z
      - .offset:         360
        .size:           8
        .value_kind:     hidden_global_offset_x
      - .offset:         368
        .size:           8
        .value_kind:     hidden_global_offset_y
      - .offset:         376
        .size:           8
        .value_kind:     hidden_global_offset_z
      - .offset:         384
        .size:           2
        .value_kind:     hidden_grid_dims
      - .offset:         440
        .size:           4
        .value_kind:     hidden_dynamic_lds_size
    .group_segment_fixed_size: 0
    .kernarg_segment_align: 8
    .kernarg_segment_size: 576
    .language:       OpenCL C
    .language_version:
      - 2
      - 0
    .max_flat_workgroup_size: 512
    .name:           _Z10fwd_kernel4Args
    .private_segment_fixed_size: 0
    .sgpr_count:     104
    .sgpr_spill_count: 15
    .symbol:         _Z10fwd_kernel4Args.kd
    .uniform_work_group_size: 1
    .uses_dynamic_stack: false
    .vgpr_count:     256
    .vgpr_spill_count: 0
    .wavefront_size: 64
